# attention block prologue: 4 q-rope fragment loads issued with the 8 q-nope loads (one wait instead of four); on top of v40
# speedup vs baseline: 1.0048x; 1.0048x over previous
.LBB0_613:
	s_and_b64 s[0:1], s[88:89], exec
	v_readlane_b32 s0, v252, 21
	v_readlane_b32 s1, v252, 25
	s_cselect_b32 s92, s0, s1
	v_readlane_b32 s0, v252, 13
	v_readlane_b32 s1, v252, 14
	s_add_i32 s82, s92, s0
	v_readlane_b32 s0, v252, 62
	v_readlane_b32 s1, v252, 63
	s_or_b32 s74, s92, s78
	s_lshr_b32 s81, s92, 6
	s_and_b64 vcc, exec, s[0:1]
	s_mov_b64 s[2:3], -1
	s_cbranch_vccz .LBB0_796
	v_mbcnt_lo_u32_b32 v190, -1, 0
	v_mbcnt_hi_u32_b32 v190, -1, v190
	v_readlane_b32 s0, v252, 17
	v_and_b32_e32 v189, 63, v190
	s_waitcnt vmcnt(0)
	v_lshlrev_b32_e32 v42, 4, v189
	v_or_b32_e32 v0, s0, v42
	s_mov_b32 s0, 0x51eb851f
	v_mul_hi_i32 v2, v0, s0
	v_lshrrev_b32_e32 v3, 31, v2
	v_ashrrev_i32_e32 v2, 7, v2
	v_add_u32_e32 v2, v2, v3
	v_and_b32_e32 v35, 63, v2
	v_mul_i32_i24_e32 v2, 0x190, v2
	v_sub_u32_e32 v2, v0, v2
	s_movk_i32 s1, 0x180
	v_ashrrev_i32_e32 v3, 4, v2
	v_cmp_gt_i32_e32 vcc, s1, v2
	v_readlane_b32 s2, v251, 49
	v_lshlrev_b32_e32 v43, 3, v189
	v_cndmask_b32_e32 v2, 0, v3, vcc
	v_cmp_lt_i32_e32 vcc, 15, v2
	v_mov_b32_e32 v4, s2
	v_or_b32_e32 v3, s78, v35
	v_cndmask_b32_e32 v5, v4, v181, vcc
	v_cndmask_b32_e64 v198, 12, 7, vcc
	v_lshl_add_u32 v200, v2, 4, v5
	v_add_u32_e32 v2, 0x2000, v0
	v_lshl_add_u32 v11, v3, v198, v200
	v_mul_hi_i32 v3, v2, s0
	v_lshrrev_b32_e32 v5, 31, v3
	v_ashrrev_i32_e32 v3, 7, v3
	v_add_u32_e32 v3, v3, v5
	v_and_b32_e32 v36, 63, v3
	v_mul_i32_i24_e32 v3, 0x190, v3
	v_sub_u32_e32 v2, v2, v3
	v_cndmask_b32_e32 v10, v248, v236, vcc
	v_ashrrev_i32_e32 v3, 4, v2
	v_cmp_gt_i32_e32 vcc, s1, v2
	v_add_u32_e32 v0, 0x4000, v0
	v_and_b32_e32 v39, 32, v190
	v_cndmask_b32_e32 v2, 0, v3, vcc
	v_cmp_lt_i32_e32 vcc, 15, v2
	v_and_b32_e32 v40, 24, v43
	v_bfe_u32 v191, v190, 5, 1
	v_cndmask_b32_e32 v3, v4, v181, vcc
	v_lshl_add_u32 v202, v2, 4, v3
	v_mul_hi_i32 v2, v0, s0
	v_lshrrev_b32_e32 v3, 31, v2
	v_ashrrev_i32_e32 v2, 7, v2
	v_add_u32_e32 v2, v2, v3
	v_and_b32_e32 v37, 63, v2
	v_mul_i32_i24_e32 v2, 0x190, v2
	v_sub_u32_e32 v0, v0, v2
	v_cndmask_b32_e64 v201, 12, 7, vcc
	v_cndmask_b32_e32 v12, v248, v236, vcc
	v_ashrrev_i32_e32 v2, 4, v0
	v_cmp_gt_i32_e32 vcc, s1, v0
	v_readlane_b32 s0, v250, 63
	v_and_b32_e32 v192, 31, v190
	v_cndmask_b32_e32 v0, 0, v2, vcc
	v_cmp_lt_i32_e32 vcc, 15, v0
	v_lshlrev_b32_e32 v34, 2, v191
	v_or_b32_e32 v5, s78, v36
	v_cndmask_b32_e32 v2, v4, v181, vcc
	v_lshl_add_u32 v204, v0, 4, v2
	v_add_u32_e32 v0, s0, v190
	v_bfe_u32 v38, v0, 2, 2
	v_lshrrev_b32_e32 v0, 1, v0
	v_and_b32_e32 v41, 8, v0
	v_readlane_b32 s0, v252, 1
	v_cndmask_b32_e64 v203, 12, 7, vcc
	v_or_b32_e32 v3, s78, v37
	v_or3_b32 v0, v38, s0, v41
	v_lshl_or_b32 v0, v0, 11, v39
	v_or3_b32 v0, v0, s72, v40
	v_or_b32_e32 v2, s82, v192
	v_lshlrev_b32_e32 v16, 1, v0
	v_lshl_add_u32 v13, v5, v201, v202
	v_cndmask_b32_e32 v14, v248, v236, vcc
	v_lshl_add_u32 v15, v3, v203, v204
	v_sub_u32_e32 v196, v2, v34
	v_add_u32_e32 v17, 0x1f700000, v16
	v_add_u32_e32 v18, 0x1f700080, v16
	v_add_u32_e32 v188, s70, v42
	s_setprio 1
	s_ashr_i32 s75, s74, 31
	s_lshl_b64 s[76:77], s[74:75], 12
	v_readlane_b32 s0, v252, 28
	v_readlane_b32 s2, v252, 13
	s_add_u32 s0, s0, s76
	v_readlane_b32 s1, v252, 31
	v_or_b32_e32 v0, s2, v192
	s_addc_u32 s1, s1, s77
	v_lshlrev_b64 v[2:3], 12, v[0:1]
	v_readlane_b32 s3, v252, 14
	v_lshl_add_u64 v[2:3], s[0:1], 0, v[2:3]
	s_lshl_b64 s[0:1], s[74:75], 11
	v_readlane_b32 s2, v252, 34
	v_lshlrev_b32_e32 v6, 4, v191
	v_mov_b32_e32 v7, v1
	s_add_u32 s2, s2, s0
	v_readlane_b32 s3, v252, 37
	v_lshl_add_u64 v[2:3], v[2:3], 0, v[6:7]
	v_lshlrev_b64 v[8:9], 11, v[0:1]
	s_addc_u32 s3, s3, s1
	flat_load_dwordx4 v[172:175], v[2:3]
	flat_load_dwordx4 v[168:171], v[2:3] offset:32
	flat_load_dwordx4 v[164:167], v[2:3] offset:64
	flat_load_dwordx4 v[160:163], v[2:3] offset:96
	flat_load_dwordx4 v[156:159], v[2:3] offset:128
	flat_load_dwordx4 v[152:155], v[2:3] offset:160
	flat_load_dwordx4 v[148:151], v[2:3] offset:192
	flat_load_dwordx4 v[144:147], v[2:3] offset:224
	v_lshl_add_u64 v[2:3], s[2:3], 0, v[8:9]
	v_lshl_add_u64 v[2:3], v[2:3], 0, v[6:7]
	flat_load_dwordx4 v[2:5], v[2:3]
	v_readlane_b32 s2, v252, 40
	s_add_u32 s0, s2, s0
	v_readlane_b32 s2, v252, 43
	s_addc_u32 s1, s2, s1
	v_add_u32_e32 v0, v11, v10
	s_cmp_lg_u32 0, -1
	v_lshl_add_u64 v[20:21], s[0:1], 0, v[8:9]
	v_lshl_add_u64 v[20:21], v[20:21], 0, v[6:7]
	s_mov_b32 s0, 0x29900000
	v_add_co_u32_e32 v8, vcc, s0, v20
	v_readlane_b32 s0, v250, 45
	s_nop 0
	v_addc_co_u32_e32 v9, vcc, 0, v21, vcc
	flat_load_dwordx4 v[24:27], v[8:9] offset:32
	flat_load_dwordx4 v[28:31], v[8:9] offset:64
	flat_load_dwordx4 v[44:47], v[8:9] offset:96
	s_waitcnt vmcnt(0) lgkmcnt(0)
	ds_write_b128 v188, v[2:5]
	ds_write_b128 v188, v[24:27] offset:1024
	ds_write_b128 v188, v[28:31] offset:2048
	ds_write_b128 v188, v[44:47] offset:3072
	s_mov_b32 m0, s0
	s_nop 0
	global_load_lds_dwordx4 v11, s[68:69]
	v_readlane_b32 s0, v251, 43
	s_mov_b32 m0, s0
	s_nop 0
	global_load_lds_dwordx4 v13, s[68:69]
	v_readlane_b32 s0, v253, 4
	s_mov_b32 m0, s33
	s_nop 0
	global_load_lds_dwordx4 v15, s[68:69]
	s_nop 0
	s_mov_b32 m0, s85
	s_nop 0
	global_load_lds_dwordx4 v17, s[68:69]
	s_nop 0
	s_mov_b32 m0, s0
	s_nop 0
	global_load_lds_dwordx4 v18, s[68:69]
	v_readlane_b32 s0, v251, 45
	s_waitcnt vmcnt(2)
	s_waitcnt lgkmcnt(0)
	s_barrier
	s_mov_b32 m0, s0
	s_nop 0
	global_load_lds_dwordx4 v0, s[68:69]
	v_readlane_b32 s0, v252, 9
	v_add_u32_e32 v0, v13, v12
	s_mov_b32 m0, s0
	s_nop 0
	global_load_lds_dwordx4 v0, s[68:69]
	v_readlane_b32 s0, v251, 47
	v_add_u32_e32 v0, v15, v14
	s_mov_b32 m0, s0
	s_nop 0
	global_load_lds_dwordx4 v0, s[68:69]
	v_readlane_b32 s0, v253, 7
	v_add_u32_e32 v0, 0x1f740000, v16
	s_mov_b32 m0, s0
	s_nop 0
	global_load_lds_dwordx4 v0, s[68:69]
	v_readlane_b32 s0, v253, 10
	v_add_u32_e32 v0, 0x1f740080, v16
	s_mov_b32 m0, s0
	s_nop 0
	global_load_lds_dwordx4 v0, s[68:69]
	s_cselect_b32 s0, 0, 0
	v_mul_u32_u24_e32 v0, 0x190, v192
	s_add_i32 s0, s0, 0xc000
	v_add3_u32 v205, v0, s0, v6
	ds_read_b128 v[2:5], v205 offset:0
	ds_read_b128 v[6:9], v205 offset:0x3200
	ds_read_b128 v[44:47], v205 offset:32
	ds_read_b128 v[48:51], v205 offset:0x3220
	ds_read_b128 v[52:55], v205 offset:64
	ds_read_b128 v[56:59], v205 offset:0x3240
	ds_read_b128 v[60:63], v205 offset:0x60
	ds_read_b128 v[64:67], v205 offset:0x3260
	s_nop 0
	s_waitcnt lgkmcnt(6)
	ds_read_b128 v[68:71], v205 offset:0x80
	ds_read_b128 v[72:75], v205 offset:0x3280
	s_waitcnt lgkmcnt(6)
	s_cmp_gt_u32 s82, 62
	v_mfma_f32_32x32x16_bf16 v[18:33], v[2:5], v[172:175], 0
	v_mfma_f32_32x32x16_bf16 v[2:17], v[6:9], v[172:175], 0
	v_mfma_f32_32x32x16_bf16 v[18:33], v[44:47], v[168:171], v[18:33]
	ds_read_b128 v[44:47], v205 offset:0xa0
	v_mfma_f32_32x32x16_bf16 v[2:17], v[48:51], v[168:171], v[2:17]
	ds_read_b128 v[48:51], v205 offset:0x32a0
	s_waitcnt lgkmcnt(6)
	s_nop 0
	v_mfma_f32_32x32x16_bf16 v[18:33], v[52:55], v[164:167], v[18:33]
	ds_read_b128 v[52:55], v205 offset:0xc0
	v_mfma_f32_32x32x16_bf16 v[2:17], v[56:59], v[164:167], v[2:17]
	ds_read_b128 v[56:59], v205 offset:0x32c0
	s_waitcnt lgkmcnt(6)
	s_nop 0
	v_mfma_f32_32x32x16_bf16 v[18:33], v[60:63], v[160:163], v[18:33]
	ds_read_b128 v[60:63], v205 offset:0xe0
	v_mfma_f32_32x32x16_bf16 v[2:17], v[64:67], v[160:163], v[2:17]
	ds_read_b128 v[64:67], v205 offset:0x32e0
	s_waitcnt lgkmcnt(6)
	s_nop 0
	v_mfma_f32_32x32x16_bf16 v[18:33], v[68:71], v[156:159], v[18:33]
	ds_read_b128 v[68:71], v205 offset:0x100
	v_mfma_f32_32x32x16_bf16 v[2:17], v[72:75], v[156:159], v[2:17]
	ds_read_b128 v[72:75], v205 offset:0x3300
	ds_read_b128 v[76:79], v188 offset:0
	s_waitcnt lgkmcnt(7)
	s_nop 0
	v_mfma_f32_32x32x16_bf16 v[18:33], v[44:47], v[152:155], v[18:33]
	ds_read_b128 v[44:47], v205 offset:0x120
	v_mfma_f32_32x32x16_bf16 v[2:17], v[48:51], v[152:155], v[2:17]
	ds_read_b128 v[48:51], v205 offset:0x3320
	ds_read_b128 v[80:83], v188 offset:0x400
	s_waitcnt lgkmcnt(8)
	s_nop 0
	v_mfma_f32_32x32x16_bf16 v[18:33], v[52:55], v[148:151], v[18:33]
	ds_read_b128 v[52:55], v205 offset:0x140
	v_mfma_f32_32x32x16_bf16 v[2:17], v[56:59], v[148:151], v[2:17]
	ds_read_b128 v[56:59], v205 offset:0x3340
	ds_read_b128 v[84:87], v188 offset:0x800
	s_waitcnt lgkmcnt(9)
	s_nop 0
	v_mfma_f32_32x32x16_bf16 v[18:33], v[60:63], v[144:147], v[18:33]
	ds_read_b128 v[60:63], v205 offset:0x160
	v_mfma_f32_32x32x16_bf16 v[2:17], v[64:67], v[144:147], v[2:17]
	ds_read_b128 v[64:67], v205 offset:0x3360
	ds_read_b128 v[88:91], v188 offset:0xc00
	s_waitcnt lgkmcnt(9)
	s_waitcnt lgkmcnt(6)
	s_waitcnt lgkmcnt(3)
	s_nop 0
	s_waitcnt lgkmcnt(0)
	v_mfma_f32_32x32x16_bf16 v[18:33], v[68:71], v[76:79], v[18:33]
	v_mfma_f32_32x32x16_bf16 v[2:17], v[72:75], v[76:79], v[2:17]
	v_mfma_f32_32x32x16_bf16 v[18:33], v[44:47], v[80:83], v[18:33]
	v_mfma_f32_32x32x16_bf16 v[2:17], v[48:51], v[80:83], v[2:17]
	v_mfma_f32_32x32x16_bf16 v[18:33], v[52:55], v[84:87], v[18:33]
	v_mfma_f32_32x32x16_bf16 v[2:17], v[56:59], v[84:87], v[2:17]
	v_mfma_f32_32x32x16_bf16 v[18:33], v[60:63], v[88:91], v[18:33]
	v_mfma_f32_32x32x16_bf16 v[2:17], v[64:67], v[88:91], v[2:17]
	s_cbranch_scc1 .LBB0_616
	v_cmp_gt_i32_e64 s[60:61], 26, v196
	v_cmp_gt_i32_e64 s[62:63], 27, v196
	v_cmp_gt_i32_e64 s[58:59], 25, v196
	s_and_b64 s[60:61], s[62:63], s[60:61]
	v_cmp_gt_i32_e64 s[56:57], 24, v196
	s_and_b64 s[58:59], s[60:61], s[58:59]
	v_cmp_gt_i32_e64 s[54:55], 19, v196
	s_and_b64 s[56:57], s[58:59], s[56:57]
	v_cmp_gt_i32_e64 s[52:53], 18, v196
	s_and_b64 s[54:55], s[56:57], s[54:55]
	v_cmp_gt_i32_e64 s[50:51], 17, v196
	s_and_b64 s[52:53], s[54:55], s[52:53]
	v_cmp_gt_i32_e64 s[48:49], 16, v196
	s_and_b64 s[50:51], s[52:53], s[50:51]
	v_cmp_gt_i32_e64 s[46:47], 11, v196
	s_and_b64 s[48:49], s[50:51], s[48:49]
	v_cmp_gt_i32_e64 s[44:45], 10, v196
	s_and_b64 s[46:47], s[48:49], s[46:47]
	v_cmp_gt_i32_e64 s[42:43], 9, v196
	s_and_b64 s[44:45], s[46:47], s[44:45]
	v_cmp_gt_i32_e64 s[40:41], 8, v196
	s_and_b64 s[42:43], s[44:45], s[42:43]
	v_cmp_gt_i32_e64 s[38:39], 3, v196
	s_and_b64 s[40:41], s[42:43], s[40:41]
	v_cmp_gt_i32_e64 s[36:37], 2, v196
	s_and_b64 s[38:39], s[40:41], s[38:39]
	v_cmp_gt_i32_e64 s[34:35], 1, v196
	s_and_b64 s[36:37], s[38:39], s[36:37]
	v_cmp_gt_i32_e64 s[30:31], 0, v196
	s_and_b64 s[34:35], s[36:37], s[34:35]
	s_and_b64 s[30:31], s[34:35], s[30:31]
	v_cmp_gt_i32_e64 s[28:29], 58, v196
	v_cndmask_b32_e64 v18, v18, v237, s[30:31]
	v_cmp_gt_i32_e64 s[30:31], 59, v196
	v_cmp_gt_i32_e64 s[26:27], 57, v196
	s_and_b64 s[28:29], s[30:31], s[28:29]
	v_cmp_gt_i32_e64 s[24:25], 56, v196
	s_and_b64 s[26:27], s[28:29], s[26:27]
	v_cmp_gt_i32_e64 s[22:23], 51, v196
	s_and_b64 s[24:25], s[26:27], s[24:25]
	v_cmp_gt_i32_e64 s[20:21], 50, v196
	s_and_b64 s[22:23], s[24:25], s[22:23]
	v_cmp_gt_i32_e64 s[18:19], 49, v196
	s_and_b64 s[20:21], s[22:23], s[20:21]
	v_cmp_gt_i32_e64 s[16:17], 48, v196
	s_and_b64 s[18:19], s[20:21], s[18:19]
	v_cmp_gt_i32_e64 s[14:15], 43, v196
	s_and_b64 s[16:17], s[18:19], s[16:17]
	v_cmp_gt_i32_e64 s[12:13], 42, v196
	s_and_b64 s[14:15], s[16:17], s[14:15]
	v_cmp_gt_i32_e64 s[10:11], 41, v196
	s_and_b64 s[12:13], s[14:15], s[12:13]
	v_cmp_gt_i32_e64 s[8:9], 40, v196
	s_and_b64 s[10:11], s[12:13], s[10:11]
	v_cmp_gt_i32_e64 s[6:7], 35, v196
	s_and_b64 s[8:9], s[10:11], s[8:9]
	v_cmp_gt_i32_e64 s[4:5], 34, v196
	s_and_b64 s[6:7], s[8:9], s[6:7]
	v_cmp_gt_i32_e64 s[2:3], 33, v196
	s_and_b64 s[4:5], s[6:7], s[4:5]
	v_cmp_gt_i32_e32 vcc, 32, v196
	s_and_b64 s[2:3], s[4:5], s[2:3]
	s_and_b64 vcc, s[2:3], vcc
	v_cndmask_b32_e64 v33, v33, v237, s[62:63]
	v_cndmask_b32_e64 v32, v32, v237, s[60:61]
	v_cndmask_b32_e64 v31, v31, v237, s[58:59]
	v_cndmask_b32_e64 v30, v30, v237, s[56:57]
	v_cndmask_b32_e64 v29, v29, v237, s[54:55]
	v_cndmask_b32_e64 v28, v28, v237, s[52:53]
	v_cndmask_b32_e64 v27, v27, v237, s[50:51]
	v_cndmask_b32_e64 v26, v26, v237, s[48:49]
	v_cndmask_b32_e64 v25, v25, v237, s[46:47]
	v_cndmask_b32_e64 v24, v24, v237, s[44:45]
	v_cndmask_b32_e64 v23, v23, v237, s[42:43]
	v_cndmask_b32_e64 v22, v22, v237, s[40:41]
	v_cndmask_b32_e64 v21, v21, v237, s[38:39]
	v_cndmask_b32_e64 v20, v20, v237, s[36:37]
	v_cndmask_b32_e64 v19, v19, v237, s[34:35]
	v_cndmask_b32_e64 v17, v17, v237, s[30:31]
	v_cndmask_b32_e64 v16, v16, v237, s[28:29]
	v_cndmask_b32_e64 v15, v15, v237, s[26:27]
	v_cndmask_b32_e64 v14, v14, v237, s[24:25]
	v_cndmask_b32_e64 v13, v13, v237, s[22:23]
	v_cndmask_b32_e64 v12, v12, v237, s[20:21]
	v_cndmask_b32_e64 v11, v11, v237, s[18:19]
	v_cndmask_b32_e64 v10, v10, v237, s[16:17]
	v_cndmask_b32_e64 v9, v9, v237, s[14:15]
	v_cndmask_b32_e64 v8, v8, v237, s[12:13]
	v_cndmask_b32_e64 v7, v7, v237, s[10:11]
	v_cndmask_b32_e64 v6, v6, v237, s[8:9]
	v_cndmask_b32_e64 v5, v5, v237, s[6:7]
	v_cndmask_b32_e64 v4, v4, v237, s[4:5]
	v_cndmask_b32_e64 v3, v3, v237, s[2:3]
	v_cndmask_b32_e32 v2, v2, v237, vcc

.LBB0_796:
	s_and_b64 vcc, exec, s[2:3]
	s_cbranch_vccz .LBB0_612
	s_ashr_i32 s75, s74, 31
	s_lshl_b64 s[66:67], s[74:75], 12
	v_readlane_b32 s0, v252, 28
	v_readlane_b32 s2, v252, 13
	v_mbcnt_lo_u32_b32 v147, -1, 0
	v_mbcnt_hi_u32_b32 v147, -1, v147
	s_add_u32 s0, s0, s66
	v_and_b32_e32 v150, 31, v147
	v_readlane_b32 s1, v252, 31
	v_readlane_b32 s3, v252, 14
	s_addc_u32 s1, s1, s67
	v_or_b32_e32 v0, s2, v150
	s_lshl_b64 s[2:3], s[74:75], 11
	v_readlane_b32 s4, v252, 34
	s_add_u32 s4, s4, s2
	v_readlane_b32 s5, v252, 37
	v_bfe_u32 v149, v147, 5, 1
	v_lshlrev_b64 v[8:9], 11, v[0:1]
	s_addc_u32 s5, s5, s3
	v_lshlrev_b32_e32 v2, 4, v149
	v_mov_b32_e32 v3, v1
	v_lshl_add_u64 v[4:5], s[4:5], 0, v[8:9]
	v_lshl_add_u64 v[4:5], v[4:5], 0, v[2:3]
	flat_load_dwordx4 v[4:7], v[4:5]
	v_lshlrev_b64 v[10:11], 12, v[0:1]
	v_lshl_add_u64 v[10:11], s[0:1], 0, v[10:11]
	v_readlane_b32 s0, v252, 40
	s_add_u32 s0, s0, s2
	v_readlane_b32 s1, v252, 43
	s_addc_u32 s1, s1, s3
	v_and_b32_e32 v148, 63, v147
	v_lshl_add_u64 v[8:9], s[0:1], 0, v[8:9]
	v_lshlrev_b32_e32 v34, 4, v148
	v_lshl_add_u64 v[8:9], v[8:9], 0, v[2:3]
	s_mov_b32 s0, 0x29900000
	v_add_u32_e32 v146, s70, v34
	v_lshl_add_u64 v[10:11], v[10:11], 0, v[2:3]
	v_add_co_u32_e32 v8, vcc, s0, v8
	flat_load_dwordx4 v[142:145], v[10:11]
	flat_load_dwordx4 v[138:141], v[10:11] offset:32
	flat_load_dwordx4 v[134:137], v[10:11] offset:64
	flat_load_dwordx4 v[130:133], v[10:11] offset:96
	flat_load_dwordx4 v[126:129], v[10:11] offset:128
	flat_load_dwordx4 v[122:125], v[10:11] offset:160
	flat_load_dwordx4 v[118:121], v[10:11] offset:192
	flat_load_dwordx4 v[114:117], v[10:11] offset:224
	v_addc_co_u32_e32 v9, vcc, 0, v9, vcc
	v_readlane_b32 s0, v251, 49
	flat_load_dwordx4 v[20:23], v[8:9] offset:32
	flat_load_dwordx4 v[24:27], v[8:9] offset:64
	flat_load_dwordx4 v[8:11], v[8:9] offset:96
	v_mov_b32_e32 v0, s0
	v_readlane_b32 s0, v252, 17
	s_waitcnt vmcnt(0) lgkmcnt(0)
	ds_write_b128 v146, v[4:7]
	ds_write_b128 v146, v[20:23] offset:1024
	v_or_b32_e32 v3, s0, v34
	s_mov_b32 s0, 0x51eb851f
	ds_write_b128 v146, v[24:27] offset:2048
	v_mul_hi_u32 v4, v3, s0
	v_or_b32_e32 v5, 0x2000, v3
	v_or_b32_e32 v6, 0x4000, v3
	v_lshrrev_b32_e32 v4, 7, v4
	v_mul_hi_u32 v12, v5, s0
	v_or_b32_e32 v7, 0x6000, v3
	v_mul_hi_u32 v13, v6, s0
	v_mul_u32_u24_e32 v15, 0x190, v4
	v_lshrrev_b32_e32 v12, 7, v12
	v_mul_hi_u32 v14, v7, s0
	v_lshrrev_b32_e32 v13, 7, v13
	v_sub_u32_e32 v3, v3, v15
	v_mul_u32_u24_e32 v15, 0x190, v12
	s_movk_i32 s0, 0x180
	v_mul_u32_u24_e32 v16, 0x190, v13
	v_lshrrev_b32_e32 v18, 4, v3
	v_sub_u32_e32 v5, v5, v15
	v_cmp_gt_u32_e32 vcc, s0, v3
	v_lshrrev_b32_e32 v14, 7, v14
	v_sub_u32_e32 v6, v6, v16
	v_cndmask_b32_e32 v3, 0, v18, vcc
	v_lshrrev_b32_e32 v15, 4, v5
	v_cmp_gt_u32_e32 vcc, s0, v5
	v_mul_u32_u24_e32 v17, 0x190, v14
	v_lshrrev_b32_e32 v16, 4, v6
	v_cmp_lt_u32_e64 s[4:5], 15, v3
	v_cndmask_b32_e32 v5, 0, v15, vcc
	v_cmp_gt_u32_e32 vcc, s0, v6
	v_sub_u32_e32 v7, v7, v17
	v_cndmask_b32_e64 v6, v0, v181, s[4:5]
	v_cndmask_b32_e32 v15, 0, v16, vcc
	v_cmp_lt_u32_e64 s[6:7], 15, v5
	v_or_b32_e32 v4, s78, v4
	v_lshrrev_b32_e32 v17, 4, v7
	v_cndmask_b32_e64 v158, 12, 7, s[4:5]
	v_cmp_gt_u32_e32 vcc, s0, v7
	v_cmp_lt_u32_e64 s[8:9], 15, v15
	v_lshl_add_u32 v162, v3, 4, v6
	v_cndmask_b32_e64 v3, v0, v181, s[6:7]
	v_and_or_b32 v12, v12, 63, s78
	v_cndmask_b32_e32 v7, 0, v17, vcc
	v_cndmask_b32_e64 v159, 12, 7, s[6:7]
	v_cndmask_b32_e64 v16, v0, v181, s[8:9]
	v_lshl_add_u32 v6, v4, v158, v162
	v_lshl_add_u32 v163, v5, 4, v3
	v_readlane_b32 s0, v250, 45
	v_and_or_b32 v13, v13, 63, s78
	v_cndmask_b32_e64 v160, 12, 7, s[8:9]
	v_cmp_lt_u32_e64 s[2:3], 15, v7
	v_lshl_add_u32 v164, v15, 4, v16
	v_lshl_add_u32 v5, v12, v159, v163
	v_cndmask_b32_e64 v0, v0, v181, s[2:3]
	v_lshl_add_u32 v4, v13, v160, v164
	v_and_or_b32 v14, v14, 63, s78
	v_cndmask_b32_e64 v161, 12, 7, s[2:3]
	v_lshl_add_u32 v165, v7, 4, v0
	v_lshl_add_u32 v3, v14, v161, v165
	s_waitcnt vmcnt(0) lgkmcnt(0)
	ds_write_b128 v146, v[8:11] offset:3072
	s_mov_b32 m0, s0
	s_nop 0
	global_load_lds_dwordx4 v6, s[68:69]
	v_readlane_b32 s0, v251, 43
	s_mov_b32 m0, s0
	s_nop 0
	global_load_lds_dwordx4 v5, s[68:69]
	v_readlane_b32 s0, v251, 1
	s_mov_b32 m0, s33
	s_nop 0
	global_load_lds_dwordx4 v4, s[68:69]
	v_readlane_b32 s1, v251, 2
	s_and_b64 vcc, exec, s[0:1]
	s_cbranch_vccnz .LBB0_799
	s_cmp_lg_u32 0, -1
	s_cselect_b32 s0, 0, 0
	s_add_i32 s0, s0, 0x12000
	s_mov_b32 m0, s0
	s_nop 0
	global_load_lds_dwordx4 v3, s[68:69]
